# phase 0 rmsnorm loop: nt hint on the x row loads (streamed once here)
# speedup vs baseline: 1.0084x; 1.0084x over previous
; __device__ void phase0(const Params& p, unsigned char* smem) {
;     ...
;     for (int row = blockIdx.x * 8 + wave; row < NTOK; row += 2 * rstride) {
;       const int row2 = row + rstride;
;       const bool has2 = row2 < NTOK;
;       const float4* xr = (const float4*)xrow(p, row);
;       const float4* xr2 = (const float4*)xrow(p, has2 ? row2 : row);
;       float4 v[4], w[4];
;       float ss = 0.f, ss2 = 0.f;
; #pragma unroll
;       for (int i = 0; i < 4; i++) { v[i] = xr[lane + 64 * i]; w[i] = xr2[lane + 64 * i]; }
;     ...
;         const float4 gg = ((const float4*)g)[lane + 64 * i];
.LBB0_163:
	s_or_b64 exec, exec, s[60:61]
	global_load_ushort v2, v[40:41], off offset:18
	s_mov_b32 s0, 0x8200
	v_and_b32_e32 v36, 0x3ff, v0
	s_waitcnt vmcnt(0)
	v_cmp_ne_u16_e32 vcc, 0, v2
	s_nop 1
	v_addc_co_u32_e32 v38, vcc, 0, v1, vcc
	v_cmp_gt_i32_e32 vcc, s0, v34
	s_and_saveexec_b64 s[10:11], vcc
	s_cbranch_execz .LBB0_174
	s_load_dwordx4 s[16:19], s[92:93], 0x0
	s_load_dwordx2 s[20:21], s[92:93], 0x38
	v_and_b32_e32 v2, 63, v0
	v_lshlrev_b32_e32 v3, 4, v2
	v_lshlrev_b32_e32 v4, 3, v2
	v_mov_b32_e32 v5, 0x358637bd
	v_readfirstlane_b32 s22, v34
	s_add_u32 s24, s88, 0x2020800
	s_addc_u32 s25, s89, 0
	s_mov_b32 s23, 0x800000
	s_mov_b32 s26, 1
	s_waitcnt lgkmcnt(0)
	global_load_dwordx4 v[8:11], v3, s[20:21]
	global_load_dwordx4 v[12:15], v3, s[20:21] offset:1024
	global_load_dwordx4 v[16:19], v3, s[20:21] offset:2048
	global_load_dwordx4 v[20:23], v3, s[20:21] offset:3072
	s_waitcnt vmcnt(0)
	s_add_i32 s29, s22, 0x800
	s_cmp_lt_u32 s29, 0x8200
	s_cselect_b32 s29, s29, s22
	s_cmp_lt_u32 s22, 0x8000
	s_cselect_b32 s30, s16, s18
	s_cselect_b32 s31, s17, s19
	s_cselect_b32 s34, 0, 0x8000
	s_sub_u32 s34, s22, s34
	s_mov_b32 s35, 0
	s_lshl_b64 s[34:35], s[34:35], 12
	s_add_u32 s30, s30, s34
	s_addc_u32 s31, s31, s35
	s_cmp_lt_u32 s29, 0x8000
	s_cselect_b32 s32, s16, s18
	s_cselect_b32 s33, s17, s19
	s_cselect_b32 s34, 0, 0x8000
	s_sub_u32 s34, s29, s34
	s_mov_b32 s35, 0
	s_lshl_b64 s[34:35], s[34:35], 12
	s_add_u32 s32, s32, s34
	s_addc_u32 s33, s33, s35
	global_load_dwordx4 v[64:67], v3, s[30:31] nt
	global_load_dwordx4 v[68:71], v3, s[30:31] offset:1024 nt
	global_load_dwordx4 v[72:75], v3, s[30:31] offset:2048 nt
	global_load_dwordx4 v[76:79], v3, s[30:31] offset:3072 nt
	global_load_dwordx4 v[80:83], v3, s[32:33] nt
	global_load_dwordx4 v[84:87], v3, s[32:33] offset:1024 nt
	global_load_dwordx4 v[88:91], v3, s[32:33] offset:2048 nt
	global_load_dwordx4 v[92:95], v3, s[32:33] offset:3072 nt
.Lxn_loop:
	s_add_i32 s27, s22, 0x1000
	s_cmp_lt_u32 s27, 0x8200
	s_cselect_b32 s28, 1, 0
	s_cbranch_scc0 .Lxn_nonext_a
	s_add_i32 s29, s27, 0x800
	s_cmp_lt_u32 s29, 0x8200
	s_cselect_b32 s29, s29, s27
	s_cmp_lt_u32 s27, 0x8000
	s_cselect_b32 s30, s16, s18
	s_cselect_b32 s31, s17, s19
	s_cselect_b32 s34, 0, 0x8000
	s_sub_u32 s34, s27, s34
	s_mov_b32 s35, 0
	s_lshl_b64 s[34:35], s[34:35], 12
	s_add_u32 s30, s30, s34
	s_addc_u32 s31, s31, s35
	s_cmp_lt_u32 s29, 0x8000
	s_cselect_b32 s32, s16, s18
	s_cselect_b32 s33, s17, s19
	s_cselect_b32 s34, 0, 0x8000
	s_sub_u32 s34, s29, s34
	s_mov_b32 s35, 0
	s_lshl_b64 s[34:35], s[34:35], 12
	s_add_u32 s32, s32, s34
	s_addc_u32 s33, s33, s35
	global_load_dwordx4 v[96:99], v3, s[30:31] nt
	global_load_dwordx4 v[100:103], v3, s[30:31] offset:1024 nt
	global_load_dwordx4 v[104:107], v3, s[30:31] offset:2048 nt
	global_load_dwordx4 v[108:111], v3, s[30:31] offset:3072 nt
	global_load_dwordx4 v[112:115], v3, s[32:33] nt
	global_load_dwordx4 v[116:119], v3, s[32:33] offset:1024 nt
	global_load_dwordx4 v[120:123], v3, s[32:33] offset:2048 nt
	global_load_dwordx4 v[124:127], v3, s[32:33] offset:3072 nt
	s_cmp_lg_u32 s26, 0
	s_cbranch_scc1 .Lxn_w8_a
	s_waitcnt vmcnt(16)
	s_branch .Lxn_go_a

; __device__ void phase0(const Params& p, unsigned char* smem) {
;     ...
;     for (int row = blockIdx.x * 8 + wave; row < NTOK; row += 2 * rstride) {
;       const int row2 = row + rstride;
;       const bool has2 = row2 < NTOK;
;       const float4* xr = (const float4*)xrow(p, row);
;       const float4* xr2 = (const float4*)xrow(p, has2 ? row2 : row);
;       float4 v[4], w[4];
;       float ss = 0.f, ss2 = 0.f;
; #pragma unroll
;       for (int i = 0; i < 4; i++) { v[i] = xr[lane + 64 * i]; w[i] = xr2[lane + 64 * i]; }
.Lxn_no2_a:
	s_mov_b32 s26, 0
	s_mov_b32 s22, s27
	s_cmp_lg_u32 s28, 0
	s_cbranch_scc0 .Lxn_done
	s_add_i32 s27, s22, 0x1000
	s_cmp_lt_u32 s27, 0x8200
	s_cselect_b32 s28, 1, 0
	s_cbranch_scc0 .Lxn_nonext_b
	s_add_i32 s29, s27, 0x800
	s_cmp_lt_u32 s29, 0x8200
	s_cselect_b32 s29, s29, s27
	s_cmp_lt_u32 s27, 0x8000
	s_cselect_b32 s30, s16, s18
	s_cselect_b32 s31, s17, s19
	s_cselect_b32 s34, 0, 0x8000
	s_sub_u32 s34, s27, s34
	s_mov_b32 s35, 0
	s_lshl_b64 s[34:35], s[34:35], 12
	s_add_u32 s30, s30, s34
	s_addc_u32 s31, s31, s35
	s_cmp_lt_u32 s29, 0x8000
	s_cselect_b32 s32, s16, s18
	s_cselect_b32 s33, s17, s19
	s_cselect_b32 s34, 0, 0x8000
	s_sub_u32 s34, s29, s34
	s_mov_b32 s35, 0
	s_lshl_b64 s[34:35], s[34:35], 12
	s_add_u32 s32, s32, s34
	s_addc_u32 s33, s33, s35
	global_load_dwordx4 v[64:67], v3, s[30:31] nt
	global_load_dwordx4 v[68:71], v3, s[30:31] offset:1024 nt
	global_load_dwordx4 v[72:75], v3, s[30:31] offset:2048 nt
	global_load_dwordx4 v[76:79], v3, s[30:31] offset:3072 nt
	global_load_dwordx4 v[80:83], v3, s[32:33] nt
	global_load_dwordx4 v[84:87], v3, s[32:33] offset:1024 nt
	global_load_dwordx4 v[88:91], v3, s[32:33] offset:2048 nt
	global_load_dwordx4 v[92:95], v3, s[32:33] offset:3072 nt
	s_cmp_lg_u32 s26, 0
	s_cbranch_scc1 .Lxn_w8_b
	s_waitcnt vmcnt(16)
	s_branch .Lxn_go_b
